# grid barriers: L1/acquire invalidate (buffer_inv sc1) issued at arrival instead of after release (1 WG/CU, other waves parked, polls bypass L1); + conv de-serialised, swapped-V, nop drop, preamble bur
# speedup vs baseline: 1.0186x; 1.0079x over previous
; __device__ __forceinline__ unsigned xb_ld(unsigned* p)              { return __hip_atomic_load(p, __ATOMIC_RELAXED, __HIP_MEMORY_SCOPE_AGENT); }
; __device__ __forceinline__ unsigned xb_add(unsigned* p, unsigned v) { return __hip_atomic_fetch_add(p, v, __ATOMIC_RELAXED, __HIP_MEMORY_SCOPE_AGENT); }
; #define XB_SPIN(cond, bar) do { unsigned _sp = 0; while (cond) { __builtin_amdgcn_s_sleep(1); \
;     if ((++_sp & 255u) == 0u) { if (xb_ld(&(bar)[XB_TMO])) break; if (_sp > XB_SPIN_CAP) { atomicAdd(&(bar)[XB_TMO], 1u); break; } } } } while (0)
; __device__ __forceinline__ void xcd_barrier(const XcdBarrier& b) {
;     ...
;         const unsigned old = xb_add(&bar[XB_XSUB(b.x)], 1u);
;         const unsigned gen = old / nloc;
;         if (old + 1u == (gen + 1u) * nloc) {
;             __builtin_amdgcn_fence(__ATOMIC_RELEASE, "agent");
;             asm volatile("s_waitcnt vmcnt(0)" ::: "memory");
;             const unsigned og = xb_add(&bar[XB_TOP], 1u);
;             const unsigned tg = og / nx;
;             if (og + 1u == (tg + 1u) * nx) xb_add(&bar[XB_TOPGEN], 1u);
;             else XB_SPIN(xb_ld(&bar[XB_TOPGEN]) == tg, bar);
;             __builtin_amdgcn_fence(__ATOMIC_ACQUIRE, "agent");
;             xb_add(&bar[XB_XGEN(b.x)], 1u);
;             asm volatile("s_waitcnt vmcnt(0)" ::: "memory");
;         } else {
;             XB_SPIN(xb_ld(&bar[XB_XGEN(b.x)]) == gen, bar);
;             __builtin_amdgcn_fence(__ATOMIC_ACQUIRE, "agent");
;             asm volatile("s_waitcnt vmcnt(0)" ::: "memory");
;         }
.LBB0_61:
	s_or_b64 exec, exec, s[12:13]
	v_cvt_f32_u32_e32 v4, v2
	s_waitcnt vmcnt(0)
	v_readfirstlane_b32 s0, v3
	buffer_inv sc1
	v_sub_u32_e32 v3, 0, v2
	v_rcp_iflag_f32_e32 v4, v4
	v_add_u32_e32 v5, s0, v1
	v_mul_f32_e32 v4, 0x4f7ffffe, v4
	v_cvt_u32_f32_e32 v4, v4
	v_mul_lo_u32 v1, v3, v4
	v_mul_hi_u32 v1, v4, v1
	v_add_u32_e32 v1, v4, v1
	v_mul_hi_u32 v1, v5, v1
	v_mul_lo_u32 v3, v1, v2
	v_sub_u32_e32 v3, v5, v3
	v_add_u32_e32 v4, 1, v1
	v_cmp_ge_u32_e32 vcc, v3, v2
	s_nop 1
	v_cndmask_b32_e32 v1, v1, v4, vcc
	v_sub_u32_e32 v4, v3, v2
	v_cndmask_b32_e32 v3, v3, v4, vcc
	v_add_u32_e32 v4, 1, v1
	v_cmp_ge_u32_e32 vcc, v3, v2
	v_add_u32_e32 v3, 1, v5
	s_nop 0
	v_cndmask_b32_e32 v1, v1, v4, vcc
	v_mul_lo_u32 v4, v2, v1
	v_add_u32_e32 v2, v4, v2
	v_cmp_ne_u32_e32 vcc, v3, v2
	s_and_saveexec_b64 s[4:5], vcc
	s_xor_b64 s[10:11], exec, s[4:5]
	s_cbranch_execz .LBB0_75
	s_waitcnt lgkmcnt(0)
	v_mov_b32_e32 v0, 0x2000
	global_load_dword v0, v0, s[8:9] offset:1024 sc1
	s_add_u32 s16, s8, 0x2400
	s_addc_u32 s17, s9, 0
	s_waitcnt vmcnt(0)
	v_cmp_eq_u32_e32 vcc, v0, v1
	s_and_saveexec_b64 s[12:13], vcc
	s_cbranch_execz .LBB0_74
	s_add_u32 s14, s24, 0xa0200
	s_addc_u32 s15, s25, 0
	s_mov_b32 s4, 1
	s_mov_b64 s[18:19], 0
	v_mov_b32_e32 v0, 0
	s_branch .LBB0_65

; __device__ __forceinline__ unsigned xb_ld(unsigned* p)              { return __hip_atomic_load(p, __ATOMIC_RELAXED, __HIP_MEMORY_SCOPE_AGENT); }
; #define XB_SPIN(cond, bar) do { unsigned _sp = 0; while (cond) { __builtin_amdgcn_s_sleep(1); \
;     if ((++_sp & 255u) == 0u) { if (xb_ld(&(bar)[XB_TMO])) break; if (_sp > XB_SPIN_CAP) { atomicAdd(&(bar)[XB_TMO], 1u); break; } } } } while (0)
; __device__ __forceinline__ void xcd_barrier(const XcdBarrier& b) {
;     ...
;         } else {
;             XB_SPIN(xb_ld(&bar[XB_XGEN(b.x)]) == gen, bar);
;             __builtin_amdgcn_fence(__ATOMIC_ACQUIRE, "agent");
;             asm volatile("s_waitcnt vmcnt(0)" ::: "memory");
;         }
.LBB0_74:
	s_or_b64 exec, exec, s[12:13]
	s_waitcnt vmcnt(0)
	s_waitcnt vmcnt(0)

; __device__ __forceinline__ unsigned xb_ld(unsigned* p)              { return __hip_atomic_load(p, __ATOMIC_RELAXED, __HIP_MEMORY_SCOPE_AGENT); }
; __device__ __forceinline__ unsigned xb_add(unsigned* p, unsigned v) { return __hip_atomic_fetch_add(p, v, __ATOMIC_RELAXED, __HIP_MEMORY_SCOPE_AGENT); }
; #define XB_SPIN(cond, bar) do { unsigned _sp = 0; while (cond) { __builtin_amdgcn_s_sleep(1); \
;     if ((++_sp & 255u) == 0u) { if (xb_ld(&(bar)[XB_TMO])) break; if (_sp > XB_SPIN_CAP) { atomicAdd(&(bar)[XB_TMO], 1u); break; } } } } while (0)
; __device__ __forceinline__ void xcd_barrier(const XcdBarrier& b) {
;     ...
;             __builtin_amdgcn_fence(__ATOMIC_RELEASE, "agent");
;             asm volatile("s_waitcnt vmcnt(0)" ::: "memory");
;             const unsigned og = xb_add(&bar[XB_TOP], 1u);
;             const unsigned tg = og / nx;
;             if (og + 1u == (tg + 1u) * nx) xb_add(&bar[XB_TOPGEN], 1u);
;             else XB_SPIN(xb_ld(&bar[XB_TOPGEN]) == tg, bar);
;             __builtin_amdgcn_fence(__ATOMIC_ACQUIRE, "agent");
;             xb_add(&bar[XB_XGEN(b.x)], 1u);
;             asm volatile("s_waitcnt vmcnt(0)" ::: "memory");
.LBB0_92:
	s_or_b64 exec, exec, s[10:11]
	s_mov_b64 s[10:11], exec
	v_mbcnt_lo_u32_b32 v0, s10, 0
	v_mbcnt_hi_u32_b32 v0, s11, v0
	v_cmp_eq_u32_e32 vcc, 0, v0
	s_waitcnt vmcnt(0)
	s_and_saveexec_b64 s[12:13], vcc
	s_cbranch_execz .LBB0_94
	s_bcnt1_i32_b64 s0, s[10:11]
	v_mov_b32_e32 v0, 0x2000
	v_mov_b32_e32 v1, s0
	global_atomic_add v0, v1, s[8:9] offset:1024

; __device__ __forceinline__ unsigned xb_ld(unsigned* p)              { return __hip_atomic_load(p, __ATOMIC_RELAXED, __HIP_MEMORY_SCOPE_AGENT); }
; __device__ __forceinline__ unsigned xb_add(unsigned* p, unsigned v) { return __hip_atomic_fetch_add(p, v, __ATOMIC_RELAXED, __HIP_MEMORY_SCOPE_AGENT); }
; #define XB_SPIN(cond, bar) do { unsigned _sp = 0; while (cond) { __builtin_amdgcn_s_sleep(1); \
;     if ((++_sp & 255u) == 0u) { if (xb_ld(&(bar)[XB_TMO])) break; if (_sp > XB_SPIN_CAP) { atomicAdd(&(bar)[XB_TMO], 1u); break; } } } } while (0)
; __device__ __forceinline__ void xcd_barrier(const XcdBarrier& b) {
;     ...
;         const unsigned old = xb_add(&bar[XB_XSUB(b.x)], 1u);
;         const unsigned gen = old / nloc;
;         if (old + 1u == (gen + 1u) * nloc) {
;             __builtin_amdgcn_fence(__ATOMIC_RELEASE, "agent");
;             asm volatile("s_waitcnt vmcnt(0)" ::: "memory");
;             const unsigned og = xb_add(&bar[XB_TOP], 1u);
;             const unsigned tg = og / nx;
;             if (og + 1u == (tg + 1u) * nx) xb_add(&bar[XB_TOPGEN], 1u);
;             else XB_SPIN(xb_ld(&bar[XB_TOPGEN]) == tg, bar);
;             __builtin_amdgcn_fence(__ATOMIC_ACQUIRE, "agent");
;             xb_add(&bar[XB_XGEN(b.x)], 1u);
;             asm volatile("s_waitcnt vmcnt(0)" ::: "memory");
;         } else {
;             XB_SPIN(xb_ld(&bar[XB_XGEN(b.x)]) == gen, bar);
;             __builtin_amdgcn_fence(__ATOMIC_ACQUIRE, "agent");
;             asm volatile("s_waitcnt vmcnt(0)" ::: "memory");
;         }
.LBB0_219:
	s_or_b64 exec, exec, s[14:15]
	v_cvt_f32_u32_e32 v4, v2
	s_waitcnt vmcnt(0)
	v_readfirstlane_b32 s0, v3
	buffer_inv sc1
	v_sub_u32_e32 v3, 0, v2
	v_rcp_iflag_f32_e32 v4, v4
	v_add_u32_e32 v5, s0, v1
	v_mul_f32_e32 v4, 0x4f7ffffe, v4
	v_cvt_u32_f32_e32 v4, v4
	v_mul_lo_u32 v1, v3, v4
	v_mul_hi_u32 v1, v4, v1
	v_add_u32_e32 v1, v4, v1
	v_mul_hi_u32 v1, v5, v1
	v_mul_lo_u32 v3, v1, v2
	v_sub_u32_e32 v3, v5, v3
	v_add_u32_e32 v4, 1, v1
	v_cmp_ge_u32_e32 vcc, v3, v2
	s_nop 1
	v_cndmask_b32_e32 v1, v1, v4, vcc
	v_sub_u32_e32 v4, v3, v2
	v_cndmask_b32_e32 v3, v3, v4, vcc
	v_add_u32_e32 v4, 1, v1
	v_cmp_ge_u32_e32 vcc, v3, v2
	v_add_u32_e32 v3, 1, v5
	s_nop 0
	v_cndmask_b32_e32 v1, v1, v4, vcc
	v_mul_lo_u32 v4, v2, v1
	v_add_u32_e32 v2, v4, v2
	v_cmp_ne_u32_e32 vcc, v3, v2
	s_and_saveexec_b64 s[4:5], vcc
	s_xor_b64 s[12:13], exec, s[4:5]
	s_cbranch_execz .LBB0_233
	s_waitcnt lgkmcnt(0)
	v_mov_b32_e32 v0, 0x2000
	global_load_dword v0, v0, s[10:11] offset:1024 sc1
	s_add_u32 s18, s10, 0x2400
	s_addc_u32 s19, s11, 0
	s_waitcnt vmcnt(0)
	v_cmp_eq_u32_e32 vcc, v0, v1
	s_and_saveexec_b64 s[14:15], vcc
	s_cbranch_execz .LBB0_232
	s_add_u32 s16, s24, 0xa0200
	s_addc_u32 s17, s25, 0
	s_mov_b32 s4, 1
	s_mov_b64 s[20:21], 0
	v_mov_b32_e32 v0, 0
	s_branch .LBB0_223

; __device__ __forceinline__ unsigned xb_ld(unsigned* p)              { return __hip_atomic_load(p, __ATOMIC_RELAXED, __HIP_MEMORY_SCOPE_AGENT); }
; #define XB_SPIN(cond, bar) do { unsigned _sp = 0; while (cond) { __builtin_amdgcn_s_sleep(1); \
;     if ((++_sp & 255u) == 0u) { if (xb_ld(&(bar)[XB_TMO])) break; if (_sp > XB_SPIN_CAP) { atomicAdd(&(bar)[XB_TMO], 1u); break; } } } } while (0)
; __device__ __forceinline__ void xcd_barrier(const XcdBarrier& b) {
;     ...
;         } else {
;             XB_SPIN(xb_ld(&bar[XB_XGEN(b.x)]) == gen, bar);
;             __builtin_amdgcn_fence(__ATOMIC_ACQUIRE, "agent");
;             asm volatile("s_waitcnt vmcnt(0)" ::: "memory");
;         }
.LBB0_232:
	s_or_b64 exec, exec, s[14:15]
	s_waitcnt vmcnt(0)
	s_waitcnt vmcnt(0)

; __device__ __forceinline__ unsigned xb_ld(unsigned* p)              { return __hip_atomic_load(p, __ATOMIC_RELAXED, __HIP_MEMORY_SCOPE_AGENT); }
; __device__ __forceinline__ unsigned xb_add(unsigned* p, unsigned v) { return __hip_atomic_fetch_add(p, v, __ATOMIC_RELAXED, __HIP_MEMORY_SCOPE_AGENT); }
; #define XB_SPIN(cond, bar) do { unsigned _sp = 0; while (cond) { __builtin_amdgcn_s_sleep(1); \
;     if ((++_sp & 255u) == 0u) { if (xb_ld(&(bar)[XB_TMO])) break; if (_sp > XB_SPIN_CAP) { atomicAdd(&(bar)[XB_TMO], 1u); break; } } } } while (0)
; __device__ __forceinline__ void xcd_barrier(const XcdBarrier& b) {
;     ...
;             __builtin_amdgcn_fence(__ATOMIC_RELEASE, "agent");
;             asm volatile("s_waitcnt vmcnt(0)" ::: "memory");
;             const unsigned og = xb_add(&bar[XB_TOP], 1u);
;             const unsigned tg = og / nx;
;             if (og + 1u == (tg + 1u) * nx) xb_add(&bar[XB_TOPGEN], 1u);
;             else XB_SPIN(xb_ld(&bar[XB_TOPGEN]) == tg, bar);
;             __builtin_amdgcn_fence(__ATOMIC_ACQUIRE, "agent");
;             xb_add(&bar[XB_XGEN(b.x)], 1u);
;             asm volatile("s_waitcnt vmcnt(0)" ::: "memory");
.LBB0_250:
	s_or_b64 exec, exec, s[12:13]
	s_mov_b64 s[12:13], exec
	v_mbcnt_lo_u32_b32 v0, s12, 0
	v_mbcnt_hi_u32_b32 v0, s13, v0
	v_cmp_eq_u32_e32 vcc, 0, v0
	s_waitcnt vmcnt(0)
	s_and_saveexec_b64 s[14:15], vcc
	s_cbranch_execz .LBB0_252
	s_bcnt1_i32_b64 s0, s[12:13]
	v_mov_b32_e32 v0, 0x2000
	v_mov_b32_e32 v1, s0
	global_atomic_add v0, v1, s[10:11] offset:1024

; __device__ __forceinline__ unsigned xb_ld(unsigned* p)              { return __hip_atomic_load(p, __ATOMIC_RELAXED, __HIP_MEMORY_SCOPE_AGENT); }
; __device__ __forceinline__ unsigned xb_add(unsigned* p, unsigned v) { return __hip_atomic_fetch_add(p, v, __ATOMIC_RELAXED, __HIP_MEMORY_SCOPE_AGENT); }
; #define XB_SPIN(cond, bar) do { unsigned _sp = 0; while (cond) { __builtin_amdgcn_s_sleep(1); \
;     if ((++_sp & 255u) == 0u) { if (xb_ld(&(bar)[XB_TMO])) break; if (_sp > XB_SPIN_CAP) { atomicAdd(&(bar)[XB_TMO], 1u); break; } } } } while (0)
; __device__ __forceinline__ void xcd_barrier(const XcdBarrier& b) {
;     ...
;         const unsigned old = xb_add(&bar[XB_XSUB(b.x)], 1u);
;         const unsigned gen = old / nloc;
;         if (old + 1u == (gen + 1u) * nloc) {
;             __builtin_amdgcn_fence(__ATOMIC_RELEASE, "agent");
;             asm volatile("s_waitcnt vmcnt(0)" ::: "memory");
;             const unsigned og = xb_add(&bar[XB_TOP], 1u);
;             const unsigned tg = og / nx;
;             if (og + 1u == (tg + 1u) * nx) xb_add(&bar[XB_TOPGEN], 1u);
;             else XB_SPIN(xb_ld(&bar[XB_TOPGEN]) == tg, bar);
;             __builtin_amdgcn_fence(__ATOMIC_ACQUIRE, "agent");
;             xb_add(&bar[XB_XGEN(b.x)], 1u);
;             asm volatile("s_waitcnt vmcnt(0)" ::: "memory");
;         } else {
;             XB_SPIN(xb_ld(&bar[XB_XGEN(b.x)]) == gen, bar);
;             __builtin_amdgcn_fence(__ATOMIC_ACQUIRE, "agent");
;             asm volatile("s_waitcnt vmcnt(0)" ::: "memory");
;         }
.LBB0_311:
	s_or_b64 exec, exec, s[14:15]
	v_cvt_f32_u32_e32 v4, v2
	s_waitcnt vmcnt(0)
	v_readfirstlane_b32 s0, v3
	buffer_inv sc1
	v_sub_u32_e32 v3, 0, v2
	v_rcp_iflag_f32_e32 v4, v4
	v_add_u32_e32 v5, s0, v1
	v_mul_f32_e32 v4, 0x4f7ffffe, v4
	v_cvt_u32_f32_e32 v4, v4
	v_mul_lo_u32 v1, v3, v4
	v_mul_hi_u32 v1, v4, v1
	v_add_u32_e32 v1, v4, v1
	v_mul_hi_u32 v1, v5, v1
	v_mul_lo_u32 v3, v1, v2
	v_sub_u32_e32 v3, v5, v3
	v_add_u32_e32 v4, 1, v1
	v_cmp_ge_u32_e32 vcc, v3, v2
	s_nop 1
	v_cndmask_b32_e32 v1, v1, v4, vcc
	v_sub_u32_e32 v4, v3, v2
	v_cndmask_b32_e32 v3, v3, v4, vcc
	v_add_u32_e32 v4, 1, v1
	v_cmp_ge_u32_e32 vcc, v3, v2
	v_add_u32_e32 v3, 1, v5
	s_nop 0
	v_cndmask_b32_e32 v1, v1, v4, vcc
	v_mul_lo_u32 v4, v2, v1
	v_add_u32_e32 v2, v4, v2
	v_cmp_ne_u32_e32 vcc, v3, v2
	s_and_saveexec_b64 s[4:5], vcc
	s_xor_b64 s[12:13], exec, s[4:5]
	s_cbranch_execz .LBB0_325
	s_waitcnt lgkmcnt(0)
	v_mov_b32_e32 v0, 0x2000
	global_load_dword v0, v0, s[10:11] offset:1024 sc1
	s_add_u32 s18, s10, 0x2400
	s_addc_u32 s19, s11, 0
	s_waitcnt vmcnt(0)
	v_cmp_eq_u32_e32 vcc, v0, v1
	s_and_saveexec_b64 s[14:15], vcc
	s_cbranch_execz .LBB0_324
	s_add_u32 s16, s24, 0xa0200
	s_addc_u32 s17, s25, 0
	s_mov_b32 s3, 1
	s_mov_b64 s[20:21], 0
	v_mov_b32_e32 v0, 0
	s_branch .LBB0_315

; __device__ __forceinline__ unsigned xb_ld(unsigned* p)              { return __hip_atomic_load(p, __ATOMIC_RELAXED, __HIP_MEMORY_SCOPE_AGENT); }
; __device__ __forceinline__ unsigned xb_add(unsigned* p, unsigned v) { return __hip_atomic_fetch_add(p, v, __ATOMIC_RELAXED, __HIP_MEMORY_SCOPE_AGENT); }
; #define XB_SPIN(cond, bar) do { unsigned _sp = 0; while (cond) { __builtin_amdgcn_s_sleep(1); \
;     if ((++_sp & 255u) == 0u) { if (xb_ld(&(bar)[XB_TMO])) break; if (_sp > XB_SPIN_CAP) { atomicAdd(&(bar)[XB_TMO], 1u); break; } } } } while (0)
; __device__ __forceinline__ void xcd_barrier(const XcdBarrier& b) {
;     ...
;         const unsigned old = xb_add(&bar[XB_XSUB(b.x)], 1u);
;         const unsigned gen = old / nloc;
;         if (old + 1u == (gen + 1u) * nloc) {
;             __builtin_amdgcn_fence(__ATOMIC_RELEASE, "agent");
;             asm volatile("s_waitcnt vmcnt(0)" ::: "memory");
;             const unsigned og = xb_add(&bar[XB_TOP], 1u);
;             const unsigned tg = og / nx;
;             if (og + 1u == (tg + 1u) * nx) xb_add(&bar[XB_TOPGEN], 1u);
;             else XB_SPIN(xb_ld(&bar[XB_TOPGEN]) == tg, bar);
;             __builtin_amdgcn_fence(__ATOMIC_ACQUIRE, "agent");
;             xb_add(&bar[XB_XGEN(b.x)], 1u);
;             asm volatile("s_waitcnt vmcnt(0)" ::: "memory");
;         } else {
;             XB_SPIN(xb_ld(&bar[XB_XGEN(b.x)]) == gen, bar);
;             __builtin_amdgcn_fence(__ATOMIC_ACQUIRE, "agent");
;             asm volatile("s_waitcnt vmcnt(0)" ::: "memory");
;         }
.LBB0_405:
	s_or_b64 exec, exec, s[12:13]
	v_cvt_f32_u32_e32 v4, v2
	s_waitcnt vmcnt(0)
	v_readfirstlane_b32 s0, v3
	buffer_inv sc1
	v_sub_u32_e32 v3, 0, v2
	v_rcp_iflag_f32_e32 v4, v4
	v_add_u32_e32 v5, s0, v1
	v_mul_f32_e32 v4, 0x4f7ffffe, v4
	v_cvt_u32_f32_e32 v4, v4
	v_mul_lo_u32 v1, v3, v4
	v_mul_hi_u32 v1, v4, v1
	v_add_u32_e32 v1, v4, v1
	v_mul_hi_u32 v1, v5, v1
	v_mul_lo_u32 v3, v1, v2
	v_sub_u32_e32 v3, v5, v3
	v_add_u32_e32 v4, 1, v1
	v_cmp_ge_u32_e32 vcc, v3, v2
	s_nop 1
	v_cndmask_b32_e32 v1, v1, v4, vcc
	v_sub_u32_e32 v4, v3, v2
	v_cndmask_b32_e32 v3, v3, v4, vcc
	v_add_u32_e32 v4, 1, v1
	v_cmp_ge_u32_e32 vcc, v3, v2
	v_add_u32_e32 v3, 1, v5
	s_nop 0
	v_cndmask_b32_e32 v1, v1, v4, vcc
	v_mul_lo_u32 v4, v2, v1
	v_add_u32_e32 v2, v4, v2
	v_cmp_ne_u32_e32 vcc, v3, v2
	s_and_saveexec_b64 s[4:5], vcc
	s_xor_b64 s[10:11], exec, s[4:5]
	s_cbranch_execz .LBB0_419
	s_waitcnt lgkmcnt(0)
	v_mov_b32_e32 v0, 0x2000
	global_load_dword v0, v0, s[8:9] offset:1024 sc1
	s_add_u32 s16, s8, 0x2400
	s_addc_u32 s17, s9, 0
	s_waitcnt vmcnt(0)
	v_cmp_eq_u32_e32 vcc, v0, v1
	s_and_saveexec_b64 s[12:13], vcc
	s_cbranch_execz .LBB0_418
	s_add_u32 s14, s24, 0xa0200
	s_addc_u32 s15, s25, 0
	s_mov_b32 s3, 1
	s_mov_b64 s[18:19], 0
	v_mov_b32_e32 v0, 0
	s_branch .LBB0_409

; __device__ __forceinline__ unsigned xb_ld(unsigned* p)              { return __hip_atomic_load(p, __ATOMIC_RELAXED, __HIP_MEMORY_SCOPE_AGENT); }
; __device__ __forceinline__ unsigned xb_add(unsigned* p, unsigned v) { return __hip_atomic_fetch_add(p, v, __ATOMIC_RELAXED, __HIP_MEMORY_SCOPE_AGENT); }
; #define XB_SPIN(cond, bar) do { unsigned _sp = 0; while (cond) { __builtin_amdgcn_s_sleep(1); \
;     if ((++_sp & 255u) == 0u) { if (xb_ld(&(bar)[XB_TMO])) break; if (_sp > XB_SPIN_CAP) { atomicAdd(&(bar)[XB_TMO], 1u); break; } } } } while (0)
; __device__ __forceinline__ void xcd_barrier(const XcdBarrier& b) {
;     ...
;         const unsigned old = xb_add(&bar[XB_XSUB(b.x)], 1u);
;         const unsigned gen = old / nloc;
;         if (old + 1u == (gen + 1u) * nloc) {
;             __builtin_amdgcn_fence(__ATOMIC_RELEASE, "agent");
;             asm volatile("s_waitcnt vmcnt(0)" ::: "memory");
;             const unsigned og = xb_add(&bar[XB_TOP], 1u);
;             const unsigned tg = og / nx;
;             if (og + 1u == (tg + 1u) * nx) xb_add(&bar[XB_TOPGEN], 1u);
;             else XB_SPIN(xb_ld(&bar[XB_TOPGEN]) == tg, bar);
;             __builtin_amdgcn_fence(__ATOMIC_ACQUIRE, "agent");
;             xb_add(&bar[XB_XGEN(b.x)], 1u);
;             asm volatile("s_waitcnt vmcnt(0)" ::: "memory");
;         } else {
;             XB_SPIN(xb_ld(&bar[XB_XGEN(b.x)]) == gen, bar);
;             __builtin_amdgcn_fence(__ATOMIC_ACQUIRE, "agent");
;             asm volatile("s_waitcnt vmcnt(0)" ::: "memory");
;         }
.LBB0_619:
	s_or_b64 exec, exec, s[12:13]
	v_cvt_f32_u32_e32 v4, v2
	s_waitcnt vmcnt(0)
	v_readfirstlane_b32 s0, v3
	buffer_inv sc1
	v_sub_u32_e32 v3, 0, v2
	v_rcp_iflag_f32_e32 v4, v4
	v_add_u32_e32 v5, s0, v1
	v_mul_f32_e32 v4, 0x4f7ffffe, v4
	v_cvt_u32_f32_e32 v4, v4
	v_mul_lo_u32 v1, v3, v4
	v_mul_hi_u32 v1, v4, v1
	v_add_u32_e32 v1, v4, v1
	v_mul_hi_u32 v1, v5, v1
	v_mul_lo_u32 v3, v1, v2
	v_sub_u32_e32 v3, v5, v3
	v_add_u32_e32 v4, 1, v1
	v_cmp_ge_u32_e32 vcc, v3, v2
	s_nop 1
	v_cndmask_b32_e32 v1, v1, v4, vcc
	v_sub_u32_e32 v4, v3, v2
	v_cndmask_b32_e32 v3, v3, v4, vcc
	v_add_u32_e32 v4, 1, v1
	v_cmp_ge_u32_e32 vcc, v3, v2
	v_add_u32_e32 v3, 1, v5
	s_nop 0
	v_cndmask_b32_e32 v1, v1, v4, vcc
	v_mul_lo_u32 v4, v2, v1
	v_add_u32_e32 v2, v4, v2
	v_cmp_ne_u32_e32 vcc, v3, v2
	s_and_saveexec_b64 s[0:1], vcc
	s_xor_b64 s[10:11], exec, s[0:1]
	s_cbranch_execz .LBB0_633
	s_waitcnt lgkmcnt(0)
	v_mov_b32_e32 v0, 0x2000
	global_load_dword v0, v0, s[4:5] offset:1024 sc1
	s_add_u32 s16, s4, 0x2400
	s_addc_u32 s17, s5, 0
	s_waitcnt vmcnt(0)
	v_cmp_eq_u32_e32 vcc, v0, v1
	s_and_saveexec_b64 s[12:13], vcc
	s_cbranch_execz .LBB0_632
	s_add_u32 s14, s24, 0xa0200
	s_addc_u32 s15, s25, 0
	s_mov_b32 s3, 1
	s_mov_b64 s[18:19], 0
	v_mov_b32_e32 v0, 0
	s_branch .LBB0_623

; __device__ __forceinline__ unsigned xb_ld(unsigned* p)              { return __hip_atomic_load(p, __ATOMIC_RELAXED, __HIP_MEMORY_SCOPE_AGENT); }
; __device__ __forceinline__ unsigned xb_add(unsigned* p, unsigned v) { return __hip_atomic_fetch_add(p, v, __ATOMIC_RELAXED, __HIP_MEMORY_SCOPE_AGENT); }
; #define XB_SPIN(cond, bar) do { unsigned _sp = 0; while (cond) { __builtin_amdgcn_s_sleep(1); \
;     if ((++_sp & 255u) == 0u) { if (xb_ld(&(bar)[XB_TMO])) break; if (_sp > XB_SPIN_CAP) { atomicAdd(&(bar)[XB_TMO], 1u); break; } } } } while (0)
; __device__ __forceinline__ void xcd_barrier(const XcdBarrier& b) {
;     ...
;             __builtin_amdgcn_fence(__ATOMIC_RELEASE, "agent");
;             asm volatile("s_waitcnt vmcnt(0)" ::: "memory");
;             const unsigned og = xb_add(&bar[XB_TOP], 1u);
;             const unsigned tg = og / nx;
;             if (og + 1u == (tg + 1u) * nx) xb_add(&bar[XB_TOPGEN], 1u);
;             else XB_SPIN(xb_ld(&bar[XB_TOPGEN]) == tg, bar);
;             __builtin_amdgcn_fence(__ATOMIC_ACQUIRE, "agent");
;             xb_add(&bar[XB_XGEN(b.x)], 1u);
;             asm volatile("s_waitcnt vmcnt(0)" ::: "memory");
.LBB0_650:
	s_or_b64 exec, exec, s[10:11]
	s_mov_b64 s[10:11], exec
	v_mbcnt_lo_u32_b32 v0, s10, 0
	v_mbcnt_hi_u32_b32 v0, s11, v0
	v_cmp_eq_u32_e32 vcc, 0, v0
	s_waitcnt vmcnt(0)
	s_and_saveexec_b64 s[12:13], vcc
	s_cbranch_execz .LBB0_652
	s_bcnt1_i32_b64 s0, s[10:11]
	v_mov_b32_e32 v0, 0x2000
	v_mov_b32_e32 v1, s0
	global_atomic_add v0, v1, s[4:5] offset:1024
